# attention layer1: rotated K/V tile visiting order per unit so neighbouring units share chunks in L2
# baseline (speedup 1.0000x reference)
; #define LAS __attribute__((address_space(3)))
; __device__ __forceinline__ int lane_id() { int l = __builtin_amdgcn_mbcnt_hi(~0u, __builtin_amdgcn_mbcnt_lo(~0u, 0u)); asm volatile("" : "+v"(l)); return l; }
; #define ATT_LOAD_K(KP, PITCH) do { _Pragma("unroll") for (int kb = 0; kb < 4; ++kb) { \
;         const char* kr_ = (const char*)((KP) + (size_t)(16 * kb) * (PITCH)) + (unsigned)((fr * (PITCH) + 8 * fq) * 2); kf[kb][0] = *(const bf16x8*)kr_; kf[kb][1] = *(const bf16x8*)(kr_ + 64); } } while (0)
; template <bool ISA>
; __device__ __forceinline__ void attn_unit(LAS unsigned char* lds, const AttnArgs& T, int sc, int wave, int) {
;     const int lane = lane_id();
;     const int fr = lane & 15, fq = lane >> 4;
;     const bool samp = sc >= 512;
;     const int b = samp ? sc - 512 : sc >> 8, c = samp ? 255 : (sc & 255);
;     const int row0 = samp ? MP + b * 64 : b * 16384 + c * 64;
;     constexpr int NPREV = ISA ? 8 : 2;
;     const int kc0 = (NPREV - c) > 0 ? (NPREV - c) : 0;
;     const int hd = wave, kv = wave >> 2;
;     const int qcol = ISA ? hd * 64 : 1536 + hd * 64;
;     LAS unsigned char* vst = lds + AL_V + wave * 8192;
;     const LAS float* ext = (const LAS float*)(lds + AL_EXT) + hd * 832;
;     LAS float* red = (LAS float*)(lds + AL_RED);
;     bf16x8 qf[4][2];
; #pragma unroll
;     for (int qb = 0; qb < 4; ++qb)
; #pragma unroll
;         for (int ks = 0; ks < 2; ++ks) qf[qb][ks] = *(const bf16x8*)((const char*)(T.Z + (size_t)(row0 + 16 * qb) * NIN + qcol + 32 * ks) + (unsigned)((fr * NIN + 8 * fq) * 2));
;     f32x4 o[4][4];
; #pragma unroll
;     for (int db = 0; db < 4; ++db)
; #pragma unroll
;         for (int qb = 0; qb < 4; ++qb) o[db][qb] = (f32x4){0.f, 0.f, 0.f, 0.f};
;     const float sink2 = ISA ? 0.f : T.sinks[hd] * LOG2E;
;     float mrow[4], lrow[4];
; #pragma unroll
;     for (int qb = 0; qb < 4; ++qb) { mrow[qb] = ISA ? -1e30f : sink2; lrow[qb] = 0.f; }
;     ...
;     bf16x8 kf[4][2];
;     { const bf16 *kp0, *vp0; int pitch0; ATT_TILE_PTRS(kc0, kp0, vp0, pitch0); (void)vp0; ATT_LOAD_K(kp0, pitch0); }
;     for (int kc = kc0; kc <= NPREV; ++kc) {
.LBB0_1121:
	v_and_b32_e32 v201, 15, v203
	v_and_b32_e32 v205, -16, v203
	v_mad_u32_u24 v0, v201, s58, v205
	v_lshl_add_u64 v[2:3], s[12:13], 0, v[0:1]
	s_add_i32 s36, s38, 16
	s_add_i32 s30, s38, 32
	v_mad_u64_u32 v[8:9], s[26:27], s38, v200, v[2:3]
	v_mad_u64_u32 v[16:17], s[26:27], s36, v200, v[2:3]
	v_mad_u64_u32 v[24:25], s[26:27], s30, v200, v[2:3]
	s_add_i32 s26, s38, 48
	s_nop 0
	v_mad_u64_u32 v[2:3], s[42:43], s26, v200, v[2:3]
	global_load_dwordx4 v[4:7], v[8:9], off
	s_nop 0
	global_load_dwordx4 v[8:11], v[8:9], off offset:64
	s_nop 0
	global_load_dwordx4 v[12:15], v[16:17], off
	s_nop 0
	global_load_dwordx4 v[16:19], v[16:17], off offset:64
	s_nop 0
	global_load_dwordx4 v[20:23], v[24:25], off
	s_nop 0
	global_load_dwordx4 v[24:27], v[24:25], off offset:64
	s_nop 0
	global_load_dwordx4 v[28:31], v[2:3], off
	global_load_dwordx4 v[32:35], v[2:3], off offset:64
	s_sub_i32 s27, 8, s31
	s_max_i32 s61, s27, 0
	s_sub_i32 s69, 8, s61
	s_mov_b32 s68, 0
	s_cmp_lg_u64 s[8:9], 0
	s_cbranch_scc1 .Latb_rd
	s_cmp_lt_u32 s31, 8
	s_cbranch_scc1 .Latb_rd
	s_mul_i32 s70, s31, 57
	s_lshr_b32 s70, s70, 9
	s_mul_i32 s70, s70, 9
	s_sub_i32 s70, s31, s70
	s_sub_i32 s68, 8, s70
	s_mov_b32 s61, s68
.Latb_rd:
	s_cmp_eq_u32 s31, 0
	s_cselect_b64 s[42:43], -1, 0
	s_xor_b64 s[46:47], s[8:9], -1
	s_or_b64 s[42:43], s[46:47], s[42:43]
	s_mov_b32 s39, s11
	s_mov_b64 s[44:45], -1
	s_and_b64 vcc, exec, s[42:43]
	s_cbranch_vccz .LBB0_1123
	s_min_u32 s27, s31, 8
	s_lshl_b32 s27, s27, 6
	s_sub_i32 s27, s38, s27
	s_lshl_b32 s70, s68, 6
	s_add_i32 s27, s27, s70
	s_mul_hi_i32 s31, s27, 0x1200
	s_mulk_i32 s27, 0x1200
	s_add_u32 s27, s12, s27
	s_addc_u32 s31, s13, s31
	s_add_u32 s42, s27, 0x400
	s_addc_u32 s43, s31, 0
	s_lshl_b32 s60, s10, 9
	s_lshl_b32 s46, s61, 6
	s_mov_b64 s[44:45], 0

; #define LAS __attribute__((address_space(3)))
; #define ATT_LOAD_K(KP, PITCH) do { _Pragma("unroll") for (int kb = 0; kb < 4; ++kb) { \
;         const char* kr_ = (const char*)((KP) + (size_t)(16 * kb) * (PITCH)) + (unsigned)((fr * (PITCH) + 8 * fq) * 2); kf[kb][0] = *(const bf16x8*)kr_; kf[kb][1] = *(const bf16x8*)(kr_ + 64); } } while (0)
; template <bool ISA>
; __device__ __forceinline__ void attn_unit(LAS unsigned char* lds, const AttnArgs& T, int sc, int wave, int) {
;     ...
;             const LAS float* eb = ext + (768 + 32 * qh + fr - 64 * kc - 4 * fq);
; #pragma unroll
;             for (int kb = 0; kb < 4; ++kb)
; #pragma unroll
;                 for (int q2 = 0; q2 < 2; ++q2) {
;                     f32x4 c0 = (f32x4){0.f, 0.f, 0.f, 0.f};
;                     if (ISA) { const LAS float* e = eb + (16 * q2 - 16 * kb); c0 = (f32x4){e[0], e[-1], e[-2], e[-3]}; }
;                     f32x4 t = __builtin_amdgcn_mfma_f32_16x16x32_bf16(kf[kb][0], qf[2 * qh + q2][0], c0, 0, 0, 0);
;                     s[kb][q2] = __builtin_amdgcn_mfma_f32_16x16x32_bf16(kf[kb][1], qf[2 * qh + q2][1], t, 0, 0, 0);
;                 }
;             if (qh == 1) { const int kn = kc < NPREV ? kc + 1 : kc; const bf16 *kpn, *vpn; int pitchn; ATT_TILE_PTRS(kn, kpn, vpn, pitchn); (void)vpn; ATT_LOAD_K(kpn, pitchn); }
.LBB0_1134:
	v_add_u32_e32 v164, 0x10c7c, v0
	ds_read2_b32 v[166:167], v164 offset1:1
	v_add_u32_e32 v164, 0x10c74, v0
	v_add_u32_e32 v165, 0x10cbc, v0
	v_add_u32_e32 v0, 0x10cb4, v0
	ds_read2_b32 v[168:169], v164 offset1:1
	ds_read2_b32 v[172:173], v165 offset1:1
	ds_read2_b32 v[174:175], v0 offset1:1
	s_waitcnt lgkmcnt(3)
	v_mov_b32_e32 v164, v167
	v_mov_b32_e32 v165, v166
	s_waitcnt lgkmcnt(2)
	v_mov_b32_e32 v166, v169
	v_mov_b32_e32 v167, v168
	s_add_i32 s43, s61, 1
	s_and_b64 s[44:45], s[44:45], exec
	v_mfma_f32_16x16x32_bf16 v[168:171], v[64:67], v[20:23], v[164:167]
	s_cselect_b32 s10, s43, 8
	s_cmp_lg_u32 s61, 8
	s_cbranch_scc1 .Latb_kn
	s_cmp_eq_u32 s69, 0
	s_cbranch_scc1 .Latb_kn
	s_mov_b32 s10, 0
.Latb_kn:
	s_cmp_lt_u32 s10, 8
	s_cselect_b64 s[44:45], -1, 0
	v_mfma_f32_16x16x32_bf16 v[180:183], v[60:63], v[24:27], v[168:171]
	s_lshl_b32 s10, s10, 6
	s_add_i32 s46, s10, s62
	s_and_b64 s[44:45], s[8:9], s[44:45]
	s_waitcnt lgkmcnt(1)
	v_mov_b32_e32 v168, v173
	v_mov_b32_e32 v169, v172
	s_waitcnt lgkmcnt(0)
	v_mov_b32_e32 v170, v175
	v_mov_b32_e32 v171, v174
	s_mul_hi_i32 s47, s46, 0x1200
	s_mulk_i32 s46, 0x1200
	v_mfma_f32_16x16x32_bf16 v[64:67], v[64:67], v[28:31], v[168:171]
	s_add_u32 s46, s12, s46
	s_addc_u32 s47, s13, s47
	s_add_u32 s48, s46, 0x400
	v_mfma_f32_16x16x32_bf16 v[168:171], v[60:63], v[32:35], v[64:67]
	s_addc_u32 s49, s47, 0
	s_add_i32 s46, s10, s60
	s_ashr_i32 s47, s46, 31
	v_mfma_f32_16x16x32_bf16 v[60:63], v[56:59], v[20:23], v[156:159]
	s_lshl_b64 s[46:47], s[46:47], 10
	s_add_u32 s10, s18, s46
	s_addc_u32 s46, s19, s47
	v_mfma_f32_16x16x32_bf16 v[56:59], v[56:59], v[28:31], v[164:167]
	s_and_b64 s[44:45], s[44:45], exec
	s_cselect_b32 s47, 0x200, s59
	s_cselect_b32 s45, s46, s49
	v_mfma_f32_16x16x32_bf16 v[184:187], v[52:55], v[24:27], v[60:63]
	s_cselect_b32 s44, s10, s48
	v_mad_u32_u24 v0, s47, v208, v205
	v_lshl_add_u64 v[236:237], s[44:45], 0, v[0:1]
	v_mfma_f32_16x16x32_bf16 v[164:167], v[52:55], v[32:35], v[56:59]
	s_lshl_b32 s10, s47, 5
	global_load_dwordx4 v[64:67], v0, s[44:45]
	global_load_dwordx4 v[60:63], v0, s[44:45] offset:64
	v_sub_f32_e32 v0, v136, v219
	v_mfma_f32_16x16x32_bf16 v[52:55], v[48:51], v[20:23], v[140:143]
	v_sub_f32_e32 v136, v137, v219
	v_exp_f32_e32 v235, v136
	v_sub_f32_e32 v136, v138, v219
	v_mfma_f32_16x16x32_bf16 v[48:51], v[48:51], v[28:31], v[156:159]
	v_exp_f32_e32 v0, v0
	v_mfma_f32_16x16x32_bf16 v[188:191], v[44:47], v[24:27], v[52:55]
	v_mfma_f32_16x16x32_bf16 v[172:175], v[44:47], v[32:35], v[48:51]
	v_mfma_f32_16x16x32_bf16 v[44:47], v[40:43], v[20:23], v[176:179]
	v_mfma_f32_16x16x32_bf16 v[40:43], v[40:43], v[28:31], v[140:143]
	v_mfma_f32_16x16x32_bf16 v[156:159], v[36:39], v[24:27], v[44:47]
	s_nop 1
	v_max_f32_e32 v140, v180, v180
	s_nop 2
	v_lshl_add_u64 v[44:45], v[236:237], 0, s[10:11]
	s_lshl_b32 s10, s47, 6
	v_mfma_f32_16x16x32_bf16 v[176:179], v[36:39], v[32:35], v[40:43]
	v_lshl_add_u64 v[36:37], v[236:237], 0, s[10:11]
	s_mul_i32 s10, s47, 0x60
	global_load_dwordx4 v[56:59], v[44:45], off
	global_load_dwordx4 v[52:55], v[44:45], off offset:64
	global_load_dwordx4 v[48:51], v[36:37], off
	s_nop 0
	global_load_dwordx4 v[44:47], v[36:37], off offset:64
	v_lshl_add_u64 v[36:37], v[236:237], 0, s[10:11]
	global_load_dwordx4 v[40:43], v[36:37], off
	s_nop 0
	global_load_dwordx4 v[36:39], v[36:37], off offset:64
	v_exp_f32_e32 v236, v136
	v_sub_f32_e32 v136, v139, v219
	v_exp_f32_e32 v237, v136
	v_sub_f32_e32 v136, v148, v219
	v_exp_f32_e32 v148, v136
	v_sub_f32_e32 v136, v149, v219
	v_exp_f32_e32 v149, v136
	v_sub_f32_e32 v136, v150, v219
	v_exp_f32_e32 v150, v136
	v_sub_f32_e32 v136, v151, v219
	v_exp_f32_e32 v151, v136
	v_sub_f32_e32 v136, v152, v219
	v_exp_f32_e32 v238, v136
	v_sub_f32_e32 v136, v153, v219
	v_max_f32_e32 v139, v181, v181
	v_exp_f32_e32 v239, v136
	v_sub_f32_e32 v136, v154, v219
	v_max_f32_e32 v139, v140, v139
	v_exp_f32_e32 v240, v136
	v_sub_f32_e32 v136, v155, v219
	v_max3_f32 v139, v139, v182, v183
	v_exp_f32_e32 v241, v136
	v_sub_f32_e32 v136, v160, v219
	v_max3_f32 v139, v139, v184, v185
	v_exp_f32_e32 v160, v136
	v_sub_f32_e32 v136, v161, v219
	v_max3_f32 v139, v139, v186, v187
	v_exp_f32_e32 v161, v136
	v_sub_f32_e32 v136, v162, v219
	v_max3_f32 v139, v139, v188, v189
	v_exp_f32_e32 v162, v136
	v_sub_f32_e32 v136, v163, v219
	v_max3_f32 v139, v139, v190, v191
	v_exp_f32_e32 v163, v136
	v_max3_f32 v139, v139, v156, v157
	v_max3_f32 v140, v139, v158, v159
	v_add_f32_e32 v139, 0x40c00000, v218
	v_cmp_le_f32_e32 vcc, v140, v139
	s_cmp_eq_u64 vcc, exec
	v_cvt_pk_bf16_f32 v152, v0, v235
	v_cvt_pk_bf16_f32 v153, v236, v237
	v_cvt_pk_bf16_f32 v154, v148, v149
	v_cvt_pk_bf16_f32 v155, v150, v151
	v_cvt_pk_bf16_f32 v136, v238, v239
	v_cvt_pk_bf16_f32 v137, v240, v241
	v_cvt_pk_bf16_f32 v138, v160, v161
	v_cvt_pk_bf16_f32 v139, v162, v163
	s_cbranch_scc1 .LBB0_1136
	ds_bpermute_b32 v141, v197, v140
	v_max_f32_e32 v140, v140, v140
	s_waitcnt lgkmcnt(0)
	v_max_f32_e32 v141, v141, v141
	v_max_f32_e32 v140, v140, v141
	ds_bpermute_b32 v141, v198, v140
	s_waitcnt lgkmcnt(0)
	v_max3_f32 v141, v218, v140, v141
	v_sub_f32_e32 v140, v218, v141
	v_exp_f32_e32 v140, v140
	v_mov_b32_e32 v218, v141
	v_mul_f32_e32 v206, v206, v140
	v_pk_mul_f32 v[86:87], v[86:87], v[140:141] op_sel_hi:[1,0]
	v_pk_mul_f32 v[84:85], v[84:85], v[140:141] op_sel_hi:[1,0]
	v_pk_mul_f32 v[94:95], v[94:95], v[140:141] op_sel_hi:[1,0]
	v_pk_mul_f32 v[92:93], v[92:93], v[140:141] op_sel_hi:[1,0]
	v_pk_mul_f32 v[98:99], v[98:99], v[140:141] op_sel_hi:[1,0]
	v_pk_mul_f32 v[96:97], v[96:97], v[140:141] op_sel_hi:[1,0]
	v_pk_mul_f32 v[90:91], v[90:91], v[140:141] op_sel_hi:[1,0]
	v_pk_mul_f32 v[88:89], v[88:89], v[140:141] op_sel_hi:[1,0]

; #define LAS __attribute__((address_space(3)))
; __device__ __forceinline__ unsigned cvt_pk(float lo, float hi) { unsigned r; asm("v_cvt_pk_bf16_f32 %0, %1, %2" : "=v"(r) : "v"(lo), "v"(hi)); return r; }
; __device__ __forceinline__ float fexp2(float x) { return __builtin_amdgcn_exp2f(x); }
; template <bool ISA>
; __device__ __forceinline__ void attn_unit(LAS unsigned char* lds, const AttnArgs& T, int sc, int wave, int) {
;     ...
;                 const float mcur = mrow[qb];
;                 float ps = 0.f; float p[4][4];
; #pragma unroll
;                 for (int kb = 0; kb < 4; ++kb)
; #pragma unroll
;                     for (int j = 0; j < 4; ++j) { p[kb][j] = fexp2(s[kb][q2][j] - mcur); ps += p[kb][j]; }
;                 lrow[qb] += ps;
; #pragma unroll
;                 for (int kp2 = 0; kp2 < 2; ++kp2) {
;                     v4u w; w.x = cvt_pk(p[2 * kp2][0], p[2 * kp2][1]); w.y = cvt_pk(p[2 * kp2][2], p[2 * kp2][3]);
;                     w.z = cvt_pk(p[2 * kp2 + 1][0], p[2 * kp2 + 1][1]); w.w = cvt_pk(p[2 * kp2 + 1][2], p[2 * kp2 + 1][3]);
;                     pf[qb][kp2] = __builtin_bit_cast(bf16x8, w);
;                 }
;             }
;         }
;         asm volatile("s_waitcnt vmcnt(8)" ::: "memory");
;         __builtin_amdgcn_wave_barrier();
;         const int tq = (lane & 15) >> 2, tp = lane & 3;
; #pragma unroll
;         for (int kp2 = 0; kp2 < 2; ++kp2) {
;             bf16x8 vf[4];
; #pragma unroll
;             for (int db = 0; db < 4; ++db) {
;                 const int r8 = 4 * (fq & 1) + tq;
;                 LAS unsigned char* a0 = vst + (4 * kp2 + (fq >> 1)) * 1024 + r8 * 128 + (((2 * db + (tp >> 1)) ^ (r8 & 6)) * 16) + (tp & 1) * 8;
;                 const s16x4 lo = __builtin_bit_cast(s16x4, __builtin_amdgcn_ds_read_tr16_b64_v4i16((LAS s16x4*)a0));
;                 const s16x4 hi = __builtin_bit_cast(s16x4, __builtin_amdgcn_ds_read_tr16_b64_v4i16((LAS s16x4*)(a0 + 2048)));
;                 vf[db] = (bf16x8){lo[0], lo[1], lo[2], lo[3], hi[0], hi[1], hi[2], hi[3]};
;             }
; #pragma unroll
;             for (int qb = 0; qb < 4; ++qb)
; #pragma unroll
;                 for (int db = 0; db < 4; ++db) o[db][qb] = __builtin_amdgcn_mfma_f32_16x16x32_bf16(vf[db], pf[qb][kp2], o[db][qb], 0, 0, 0);
;         }
;         asm volatile("" ::: "memory");
;     }
.LBB0_1138:
	v_add_f32_e32 v0, 0, v0
	v_add_f32_e32 v0, v235, v0
	v_add_f32_e32 v0, v236, v0
	v_add_f32_e32 v0, v237, v0
	v_add_f32_e32 v0, v148, v0
	v_add_f32_e32 v0, v149, v0
	v_add_f32_e32 v0, v150, v0
	v_add_f32_e32 v0, v151, v0
	v_add_f32_e32 v0, v238, v0
	v_add_f32_e32 v0, v239, v0
	v_add_f32_e32 v0, v240, v0
	v_add_f32_e32 v0, v241, v0
	v_add_f32_e32 v0, v160, v0
	v_add_f32_e32 v0, v161, v0
	v_add_f32_e32 v0, v162, v0
	v_add_f32_e32 v0, v163, v0
	v_add_f32_e32 v207, v207, v0
	v_add_f32_e32 v0, 0, v2
	v_add_f32_e32 v0, v3, v0
	v_add_f32_e32 v0, v221, v0
	v_add_f32_e32 v0, v222, v0
	v_add_f32_e32 v0, v223, v0
	v_add_f32_e32 v0, v224, v0
	v_add_f32_e32 v0, v225, v0
	v_add_f32_e32 v0, v226, v0
	v_add_f32_e32 v0, v227, v0
	v_add_f32_e32 v0, v228, v0
	v_add_f32_e32 v0, v229, v0
	v_add_f32_e32 v0, v230, v0
	v_add_f32_e32 v0, v231, v0
	v_add_f32_e32 v0, v232, v0
	v_add_f32_e32 v0, v233, v0
	v_add_f32_e32 v0, v234, v0
	v_add_f32_e32 v216, v216, v0
	v_sub_f32_e32 v0, v168, v217
	v_exp_f32_e32 v0, v0
	v_sub_f32_e32 v3, v169, v217
	v_exp_f32_e32 v3, v3
	v_sub_f32_e32 v148, v170, v217
	v_exp_f32_e32 v148, v148
	v_sub_f32_e32 v149, v171, v217
	v_exp_f32_e32 v149, v149
	v_sub_f32_e32 v150, v164, v217
	v_add_f32_e32 v2, 0, v0
	v_exp_f32_e32 v150, v150
	v_sub_f32_e32 v151, v165, v217
	v_add_f32_e32 v2, v3, v2
	v_exp_f32_e32 v151, v151
	v_sub_f32_e32 v160, v166, v217
	v_add_f32_e32 v2, v148, v2
	v_exp_f32_e32 v163, v160
	v_sub_f32_e32 v160, v167, v217
	v_add_f32_e32 v2, v149, v2
	v_exp_f32_e32 v164, v160
	v_sub_f32_e32 v160, v172, v217
	v_add_f32_e32 v2, v150, v2
	v_exp_f32_e32 v165, v160
	v_sub_f32_e32 v160, v173, v217
	v_add_f32_e32 v2, v151, v2
	v_exp_f32_e32 v166, v160
	v_sub_f32_e32 v160, v174, v217
	v_add_f32_e32 v2, v163, v2
	v_exp_f32_e32 v167, v160
	v_sub_f32_e32 v160, v175, v217
	v_add_f32_e32 v2, v164, v2
	v_exp_f32_e32 v168, v160
	v_sub_f32_e32 v160, v176, v217
	v_add_f32_e32 v2, v165, v2
	v_exp_f32_e32 v169, v160
	v_sub_f32_e32 v160, v177, v217
	v_add_f32_e32 v2, v166, v2
	v_exp_f32_e32 v170, v160
	v_sub_f32_e32 v160, v178, v217
	v_add_f32_e32 v2, v167, v2
	v_exp_f32_e32 v171, v160
	v_sub_f32_e32 v160, v179, v217
	v_add_f32_e32 v2, v168, v2
	v_exp_f32_e32 v172, v160
	v_add_f32_e32 v180, 0, v180
	v_add_f32_e32 v2, v169, v2
	v_add_f32_e32 v180, v181, v180
	v_add_f32_e32 v2, v170, v2
	v_add_f32_e32 v180, v182, v180
	v_add_f32_e32 v2, v171, v2
	v_add_f32_e32 v180, v183, v180
	v_add_f32_e32 v2, v172, v2
	v_cvt_pk_bf16_f32 v161, v148, v149
	v_cvt_pk_bf16_f32 v162, v150, v151
	v_cvt_pk_bf16_f32 v163, v163, v164
	v_cvt_pk_bf16_f32 v148, v165, v166
	v_cvt_pk_bf16_f32 v149, v167, v168
	v_cvt_pk_bf16_f32 v150, v169, v170
	v_cvt_pk_bf16_f32 v151, v171, v172
	s_waitcnt vmcnt(8)
	ds_read_b64_tr_b16 v[164:165], v212
	ds_read_b64_tr_b16 v[166:167], v212 offset:2048
	ds_read_b64_tr_b16 v[168:169], v213
	ds_read_b64_tr_b16 v[170:171], v213 offset:2048
	ds_read_b64_tr_b16 v[172:173], v214
	ds_read_b64_tr_b16 v[174:175], v214 offset:2048
	ds_read_b64_tr_b16 v[176:177], v215
	ds_read_b64_tr_b16 v[178:179], v215 offset:2048
	v_add_f32_e32 v180, v184, v180
	v_add_f32_e32 v180, v185, v180
	v_add_f32_e32 v180, v186, v180
	v_add_f32_e32 v180, v187, v180
	v_cvt_pk_bf16_f32 v160, v0, v3
	v_add_f32_e32 v180, v188, v180
	s_waitcnt lgkmcnt(6)
	v_mfma_f32_16x16x32_bf16 v[116:119], v[164:167], v[144:147], v[116:119]
	v_add_f32_e32 v180, v189, v180
	v_add_f32_e32 v180, v190, v180
	v_add_f32_e32 v180, v191, v180
	s_waitcnt lgkmcnt(4)
	v_mfma_f32_16x16x32_bf16 v[124:127], v[168:171], v[144:147], v[124:127]
	v_add_f32_e32 v180, v242, v180
	v_add_f32_e32 v180, v243, v180
	v_add_f32_e32 v180, v244, v180
	s_waitcnt lgkmcnt(2)
	v_mfma_f32_16x16x32_bf16 v[128:131], v[172:175], v[144:147], v[128:131]
	v_add_f32_e32 v180, v245, v180
	s_addk_i32 s66, 0xff00
	s_add_i32 s65, s65, 64
	s_waitcnt lgkmcnt(0)
	v_mfma_f32_16x16x32_bf16 v[120:123], v[176:179], v[144:147], v[120:123]
	s_add_i32 s42, s42, 64
	v_add_f32_e32 v206, v206, v180
	v_add_f32_e32 v204, v204, v2
	v_mfma_f32_16x16x32_bf16 v[100:103], v[164:167], v[152:155], v[100:103]
	s_cmp_eq_u32 s69, 0
	v_mfma_f32_16x16x32_bf16 v[108:111], v[168:171], v[152:155], v[108:111]
	v_mfma_f32_16x16x32_bf16 v[112:115], v[172:175], v[152:155], v[112:115]
	v_mfma_f32_16x16x32_bf16 v[104:107], v[176:179], v[152:155], v[104:107]
	v_mfma_f32_16x16x32_bf16 v[84:87], v[164:167], v[156:159], v[84:87]
	v_mfma_f32_16x16x32_bf16 v[92:95], v[168:171], v[156:159], v[92:95]
	v_mfma_f32_16x16x32_bf16 v[96:99], v[172:175], v[156:159], v[96:99]
	v_mfma_f32_16x16x32_bf16 v[88:91], v[176:179], v[156:159], v[88:91]
	v_mfma_f32_16x16x32_bf16 v[68:71], v[164:167], v[160:163], v[68:71]
	v_mfma_f32_16x16x32_bf16 v[76:79], v[168:171], v[160:163], v[76:79]
	v_mfma_f32_16x16x32_bf16 v[80:83], v[172:175], v[160:163], v[80:83]
	v_mfma_f32_16x16x32_bf16 v[72:75], v[176:179], v[160:163], v[72:75]
	ds_read_b64_tr_b16 v[152:153], v212 offset:4096
	ds_read_b64_tr_b16 v[154:155], v212 offset:6144
	ds_read_b64_tr_b16 v[160:161], v213 offset:4096
	ds_read_b64_tr_b16 v[162:163], v213 offset:6144
	ds_read_b64_tr_b16 v[156:157], v214 offset:4096
	ds_read_b64_tr_b16 v[158:159], v214 offset:6144
	ds_read_b64_tr_b16 v[144:145], v215 offset:4096
	ds_read_b64_tr_b16 v[146:147], v215 offset:6144
	s_waitcnt lgkmcnt(6)
	v_mfma_f32_16x16x32_bf16 v[116:119], v[152:155], v[132:135], v[116:119]
	s_waitcnt lgkmcnt(4)
	v_mfma_f32_16x16x32_bf16 v[124:127], v[160:163], v[132:135], v[124:127]
	s_waitcnt lgkmcnt(2)
	v_mfma_f32_16x16x32_bf16 v[128:131], v[156:159], v[132:135], v[128:131]
	s_waitcnt lgkmcnt(0)
	v_mfma_f32_16x16x32_bf16 v[120:123], v[144:147], v[132:135], v[120:123]
	v_mfma_f32_16x16x32_bf16 v[100:103], v[152:155], v[136:139], v[100:103]
	v_mfma_f32_16x16x32_bf16 v[108:111], v[160:163], v[136:139], v[108:111]
	v_mfma_f32_16x16x32_bf16 v[112:115], v[156:159], v[136:139], v[112:115]
	v_mfma_f32_16x16x32_bf16 v[104:107], v[144:147], v[136:139], v[104:107]
	v_mfma_f32_16x16x32_bf16 v[84:87], v[152:155], v[140:143], v[84:87]
	v_mfma_f32_16x16x32_bf16 v[92:95], v[160:163], v[140:143], v[92:95]
	v_mfma_f32_16x16x32_bf16 v[96:99], v[156:159], v[140:143], v[96:99]
	v_mfma_f32_16x16x32_bf16 v[88:91], v[144:147], v[140:143], v[88:91]
	v_mfma_f32_16x16x32_bf16 v[68:71], v[152:155], v[148:151], v[68:71]
	v_mfma_f32_16x16x32_bf16 v[76:79], v[160:163], v[148:151], v[76:79]
	v_mfma_f32_16x16x32_bf16 v[80:83], v[156:159], v[148:151], v[80:83]
	v_mfma_f32_16x16x32_bf16 v[72:75], v[144:147], v[148:151], v[72:75]
	s_cbranch_scc1 .LBB0_1140
	s_add_i32 s69, s69, -1
	s_mov_b32 s61, s43
	s_cmp_lt_u32 s61, 9
	s_cbranch_scc1 .Latb_nw
	s_mov_b32 s61, 0
	s_addk_i32 s66, 0x900
	s_addk_i32 s65, 0xfdc0
	s_addk_i32 s42, 0xfdc0
.Latb_nw:
	s_branch .LBB0_1126
